# grid seams: the second-to-last workgroup to arrive on an XCD starts the L2 write-back early (unwaited by the others), leaving the leader's write-back little to do
# baseline (speedup 1.0000x reference)
; __device__ __forceinline__ unsigned xb_ld(unsigned* p)              { return __hip_atomic_load(p, __ATOMIC_RELAXED, __HIP_MEMORY_SCOPE_AGENT); }
; __device__ __forceinline__ unsigned xb_add(unsigned* p, unsigned v) { return __hip_atomic_fetch_add(p, v, __ATOMIC_RELAXED, __HIP_MEMORY_SCOPE_AGENT); }
; #define XB_SPIN(cond, bar) do { unsigned _sp = 0; while (cond) { __builtin_amdgcn_s_sleep(1); \
;     if ((++_sp & 255u) == 0u) { if (xb_ld(&(bar)[XB_TMO])) break; if (_sp > XB_SPIN_CAP) { atomicAdd(&(bar)[XB_TMO], 1u); break; } } } } while (0)
; __device__ __forceinline__ void xcd_barrier(const XcdBarrier& b, const int wv) {
;     ...
;         const unsigned old = xb_add(&bar[XB_XSUB(b.x)], 1u);
;         const unsigned gen = old / nloc;
;         if (old + 1u == (gen + 1u) * nloc) {
;             __builtin_amdgcn_fence(__ATOMIC_RELEASE, "agent");
;             asm volatile("s_waitcnt vmcnt(0)" ::: "memory");
;             const unsigned og = xb_add(&bar[XB_TOP], 1u);
;             const unsigned tg = og / nx;
;             if (og + 1u == (tg + 1u) * nx) xb_add(&bar[XB_TOPGEN], 1u);
;             else XB_SPIN(xb_ld(&bar[XB_TOPGEN]) == tg, bar);
;             __builtin_amdgcn_fence(__ATOMIC_ACQUIRE, "agent");
;             xb_add(&bar[XB_XGEN(b.x)], 1u);
;             asm volatile("s_waitcnt vmcnt(0)" ::: "memory");
;         } else {
;             XB_SPIN(xb_ld(&bar[XB_XGEN(b.x)]) == gen, bar);
;             __builtin_amdgcn_fence(__ATOMIC_ACQUIRE, "agent");
;             asm volatile("s_waitcnt vmcnt(0)" ::: "memory");
;         }
.Lseam1_328:
	s_or_b64 exec, exec, s[14:15]
	v_cvt_f32_u32_e32 v4, v2
	s_waitcnt vmcnt(0)
	v_readfirstlane_b32 s3, v3
	v_sub_u32_e32 v3, 0, v2
	v_rcp_iflag_f32_e32 v4, v4
	v_add_u32_e32 v5, s3, v1
	v_mul_f32_e32 v4, 0x4f7ffffe, v4
	v_cvt_u32_f32_e32 v4, v4
	v_mul_lo_u32 v1, v3, v4
	v_mul_hi_u32 v1, v4, v1
	v_add_u32_e32 v1, v4, v1
	v_mul_hi_u32 v1, v5, v1
	v_mul_lo_u32 v3, v1, v2
	v_sub_u32_e32 v3, v5, v3
	v_add_u32_e32 v4, 1, v1
	v_cmp_ge_u32_e32 vcc, v3, v2
	s_nop 1
	v_cndmask_b32_e32 v1, v1, v4, vcc
	v_sub_u32_e32 v4, v3, v2
	v_cndmask_b32_e32 v3, v3, v4, vcc
	v_add_u32_e32 v4, 1, v1
	v_cmp_ge_u32_e32 vcc, v3, v2
	v_add_u32_e32 v3, 1, v5
	s_nop 0
	v_cndmask_b32_e32 v1, v1, v4, vcc
	v_mul_lo_u32 v4, v2, v1
	v_add_u32_e32 v2, v4, v2
	v_cmp_ne_u32_e32 vcc, v3, v2
	s_and_saveexec_b64 s[12:13], vcc
	s_xor_b64 s[12:13], exec, s[12:13]
	s_cbranch_execz .Lseam1_342
	v_add_u32_e32 v19, 1, v3
	v_cmp_eq_u32_e32 vcc, v19, v2
	s_cbranch_vccz .Lpf2_0
	buffer_wbl2 sc1
.Lpf2_0:
	s_waitcnt lgkmcnt(0)
	v_mov_b32_e32 v0, 0x2000
	global_load_dword v0, v0, s[10:11] offset:1024 sc1
	s_add_u32 s18, s10, 0x2400
	s_addc_u32 s19, s11, 0
	s_waitcnt vmcnt(0)
	v_cmp_eq_u32_e32 vcc, v0, v1
	s_and_saveexec_b64 s[14:15], vcc
	s_cbranch_execz .Lseam1_341
	s_add_u32 s16, s6, 0x4200
	s_addc_u32 s17, s7, 0
	s_mov_b32 s3, 1
	s_mov_b64 s[20:21], 0
	v_mov_b32_e32 v0, 0
	s_branch .Lseam1_332

; __device__ __forceinline__ unsigned xb_ld(unsigned* p)              { return __hip_atomic_load(p, __ATOMIC_RELAXED, __HIP_MEMORY_SCOPE_AGENT); }
; __device__ __forceinline__ unsigned xb_add(unsigned* p, unsigned v) { return __hip_atomic_fetch_add(p, v, __ATOMIC_RELAXED, __HIP_MEMORY_SCOPE_AGENT); }
; #define XB_SPIN(cond, bar) do { unsigned _sp = 0; while (cond) { __builtin_amdgcn_s_sleep(1); \
;     if ((++_sp & 255u) == 0u) { if (xb_ld(&(bar)[XB_TMO])) break; if (_sp > XB_SPIN_CAP) { atomicAdd(&(bar)[XB_TMO], 1u); break; } } } } while (0)
; __device__ __forceinline__ void xcd_barrier(const XcdBarrier& b, const int wv) {
;     ...
;         const unsigned old = xb_add(&bar[XB_XSUB(b.x)], 1u);
;         const unsigned gen = old / nloc;
;         if (old + 1u == (gen + 1u) * nloc) {
;             __builtin_amdgcn_fence(__ATOMIC_RELEASE, "agent");
;             asm volatile("s_waitcnt vmcnt(0)" ::: "memory");
;             const unsigned og = xb_add(&bar[XB_TOP], 1u);
;             const unsigned tg = og / nx;
;             if (og + 1u == (tg + 1u) * nx) xb_add(&bar[XB_TOPGEN], 1u);
;             else XB_SPIN(xb_ld(&bar[XB_TOPGEN]) == tg, bar);
;             __builtin_amdgcn_fence(__ATOMIC_ACQUIRE, "agent");
;             xb_add(&bar[XB_XGEN(b.x)], 1u);
;             asm volatile("s_waitcnt vmcnt(0)" ::: "memory");
;         } else {
;             XB_SPIN(xb_ld(&bar[XB_XGEN(b.x)]) == gen, bar);
;             __builtin_amdgcn_fence(__ATOMIC_ACQUIRE, "agent");
;             asm volatile("s_waitcnt vmcnt(0)" ::: "memory");
;         }
.LBB0_727:
	s_or_b64 exec, exec, s[16:17]
	v_cvt_f32_u32_e32 v4, v2
	s_waitcnt vmcnt(0)
	v_readfirstlane_b32 s3, v3
	v_sub_u32_e32 v3, 0, v2
	v_rcp_iflag_f32_e32 v4, v4
	v_add_u32_e32 v5, s3, v1
	v_mul_f32_e32 v4, 0x4f7ffffe, v4
	v_cvt_u32_f32_e32 v4, v4
	v_mul_lo_u32 v1, v3, v4
	v_mul_hi_u32 v1, v4, v1
	v_add_u32_e32 v1, v4, v1
	v_mul_hi_u32 v1, v5, v1
	v_mul_lo_u32 v3, v1, v2
	v_sub_u32_e32 v3, v5, v3
	v_add_u32_e32 v4, 1, v1
	v_cmp_ge_u32_e32 vcc, v3, v2
	s_nop 1
	v_cndmask_b32_e32 v1, v1, v4, vcc
	v_sub_u32_e32 v4, v3, v2
	v_cndmask_b32_e32 v3, v3, v4, vcc
	v_add_u32_e32 v4, 1, v1
	v_cmp_ge_u32_e32 vcc, v3, v2
	v_add_u32_e32 v3, 1, v5
	s_nop 0
	v_cndmask_b32_e32 v1, v1, v4, vcc
	v_mul_lo_u32 v4, v2, v1
	v_add_u32_e32 v2, v4, v2
	v_cmp_ne_u32_e32 vcc, v3, v2
	s_and_saveexec_b64 s[14:15], vcc
	s_xor_b64 s[14:15], exec, s[14:15]
	s_cbranch_execz .LBB0_741
	v_add_u32_e32 v19, 1, v3
	v_cmp_eq_u32_e32 vcc, v19, v2
	s_cbranch_vccz .Lpf2_4
	buffer_wbl2 sc1
.Lpf2_4:
	s_waitcnt lgkmcnt(0)
	v_mov_b32_e32 v0, 0x2000
	global_load_dword v0, v0, s[12:13] offset:1024 sc1
	s_add_u32 s20, s12, 0x2400
	s_addc_u32 s21, s13, 0
	s_waitcnt vmcnt(0)
	v_cmp_eq_u32_e32 vcc, v0, v1
	s_and_saveexec_b64 s[16:17], vcc
	s_cbranch_execz .LBB0_740
	s_add_u32 s18, s10, 0x4200
	s_addc_u32 s19, s11, 0
	s_mov_b32 s3, 1
	s_mov_b64 s[22:23], 0
	v_mov_b32_e32 v0, 0
	s_branch .LBB0_731

; __device__ __forceinline__ unsigned xb_ld(unsigned* p)              { return __hip_atomic_load(p, __ATOMIC_RELAXED, __HIP_MEMORY_SCOPE_AGENT); }
; __device__ __forceinline__ unsigned xb_add(unsigned* p, unsigned v) { return __hip_atomic_fetch_add(p, v, __ATOMIC_RELAXED, __HIP_MEMORY_SCOPE_AGENT); }
; #define XB_SPIN(cond, bar) do { unsigned _sp = 0; while (cond) { __builtin_amdgcn_s_sleep(1); \
;     if ((++_sp & 255u) == 0u) { if (xb_ld(&(bar)[XB_TMO])) break; if (_sp > XB_SPIN_CAP) { atomicAdd(&(bar)[XB_TMO], 1u); break; } } } } while (0)
; __device__ __forceinline__ void xcd_barrier(const XcdBarrier& b, const int wv) {
;     ...
;         const unsigned old = xb_add(&bar[XB_XSUB(b.x)], 1u);
;         const unsigned gen = old / nloc;
;         if (old + 1u == (gen + 1u) * nloc) {
;             __builtin_amdgcn_fence(__ATOMIC_RELEASE, "agent");
;             asm volatile("s_waitcnt vmcnt(0)" ::: "memory");
;             const unsigned og = xb_add(&bar[XB_TOP], 1u);
;             const unsigned tg = og / nx;
;             if (og + 1u == (tg + 1u) * nx) xb_add(&bar[XB_TOPGEN], 1u);
;             else XB_SPIN(xb_ld(&bar[XB_TOPGEN]) == tg, bar);
;             __builtin_amdgcn_fence(__ATOMIC_ACQUIRE, "agent");
;             xb_add(&bar[XB_XGEN(b.x)], 1u);
;             asm volatile("s_waitcnt vmcnt(0)" ::: "memory");
;         } else {
;             XB_SPIN(xb_ld(&bar[XB_XGEN(b.x)]) == gen, bar);
;             __builtin_amdgcn_fence(__ATOMIC_ACQUIRE, "agent");
;             asm volatile("s_waitcnt vmcnt(0)" ::: "memory");
;         }
.LBB0_860:
	s_or_b64 exec, exec, s[18:19]
	v_cvt_f32_u32_e32 v4, v2
	s_waitcnt vmcnt(0)
	v_readfirstlane_b32 s3, v3
	v_sub_u32_e32 v3, 0, v2
	v_rcp_iflag_f32_e32 v4, v4
	v_add_u32_e32 v5, s3, v1
	v_mul_f32_e32 v4, 0x4f7ffffe, v4
	v_cvt_u32_f32_e32 v4, v4
	v_mul_lo_u32 v1, v3, v4
	v_mul_hi_u32 v1, v4, v1
	v_add_u32_e32 v1, v4, v1
	v_mul_hi_u32 v1, v5, v1
	v_mul_lo_u32 v3, v1, v2
	v_sub_u32_e32 v3, v5, v3
	v_add_u32_e32 v4, 1, v1
	v_cmp_ge_u32_e32 vcc, v3, v2
	s_nop 1
	v_cndmask_b32_e32 v1, v1, v4, vcc
	v_sub_u32_e32 v4, v3, v2
	v_cndmask_b32_e32 v3, v3, v4, vcc
	v_add_u32_e32 v4, 1, v1
	v_cmp_ge_u32_e32 vcc, v3, v2
	v_add_u32_e32 v3, 1, v5
	s_nop 0
	v_cndmask_b32_e32 v1, v1, v4, vcc
	v_mul_lo_u32 v4, v2, v1
	v_add_u32_e32 v2, v4, v2
	v_cmp_ne_u32_e32 vcc, v3, v2
	s_and_saveexec_b64 s[16:17], vcc
	s_xor_b64 s[16:17], exec, s[16:17]
	s_cbranch_execz .LBB0_874
	v_add_u32_e32 v19, 1, v3
	v_cmp_eq_u32_e32 vcc, v19, v2
	s_cbranch_vccz .Lpf2_6
	buffer_wbl2 sc1
.Lpf2_6:
	s_waitcnt lgkmcnt(0)
	v_mov_b32_e32 v0, 0x2000
	global_load_dword v0, v0, s[14:15] offset:1024 sc1
	s_add_u32 s22, s14, 0x2400
	s_addc_u32 s23, s15, 0
	s_waitcnt vmcnt(0)
	v_cmp_eq_u32_e32 vcc, v0, v1
	s_and_saveexec_b64 s[18:19], vcc
	s_cbranch_execz .LBB0_873
	s_add_u32 s20, s12, 0x4200
	s_addc_u32 s21, s13, 0
	s_mov_b32 s3, 1
	s_mov_b64 s[24:25], 0
	v_mov_b32_e32 v0, 0
	s_branch .LBB0_864

; __device__ __forceinline__ unsigned xb_ld(unsigned* p)              { return __hip_atomic_load(p, __ATOMIC_RELAXED, __HIP_MEMORY_SCOPE_AGENT); }
; #define XB_SPIN(cond, bar) do { unsigned _sp = 0; while (cond) { __builtin_amdgcn_s_sleep(1); \
;     if ((++_sp & 255u) == 0u) { if (xb_ld(&(bar)[XB_TMO])) break; if (_sp > XB_SPIN_CAP) { atomicAdd(&(bar)[XB_TMO], 1u); break; } } } } while (0)
; __device__ __forceinline__ void xcd_barrier(const XcdBarrier& b, const int wv) {
;     ...
;         } else {
;             XB_SPIN(xb_ld(&bar[XB_XGEN(b.x)]) == gen, bar);
;             __builtin_amdgcn_fence(__ATOMIC_ACQUIRE, "agent");
.Lpf2_16:
	s_waitcnt lgkmcnt(0)
	v_mov_b32_e32 v0, 0x2000
	global_load_dword v0, v0, s[10:11] offset:1024 sc1
	s_add_u32 s18, s10, 0x2400
	s_addc_u32 s19, s11, 0
	s_waitcnt vmcnt(0)
	v_cmp_eq_u32_e32 vcc, v0, v1
	s_and_saveexec_b64 s[14:15], vcc
	s_cbranch_execz .LBB0_2060
	s_add_u32 s16, s8, 0x4200
	s_addc_u32 s17, s9, 0
	s_mov_b32 s3, 1
	s_mov_b64 s[20:21], 0
	v_mov_b32_e32 v0, 0
	s_branch .LBB0_2050
